# SwiGLU epilogue with packed f32 mul/add (two elements per instruction), stage by stage; same per-element operations
# speedup vs baseline: 1.0036x; 1.0007x over previous
.LBB0_1005:
	s_mov_b32 s100, 0xbfb8aa3b
	v_pk_mul_f32 v[220:221], v[122:123], s[100:101] op_sel_hi:[1,0]
	v_pk_mul_f32 v[222:223], v[124:125], s[100:101] op_sel_hi:[1,0]
	v_pk_mul_f32 v[224:225], v[126:127], s[100:101] op_sel_hi:[1,0]
	v_pk_mul_f32 v[226:227], v[128:129], s[100:101] op_sel_hi:[1,0]
	v_exp_f32_e32 v220, v220
	v_exp_f32_e32 v221, v221
	v_exp_f32_e32 v222, v222
	v_exp_f32_e32 v223, v223
	v_exp_f32_e32 v224, v224
	v_exp_f32_e32 v225, v225
	v_exp_f32_e32 v226, v226
	v_exp_f32_e32 v227, v227
	v_pk_add_f32 v[220:221], v[220:221], 1.0 op_sel_hi:[1,0]
	v_pk_add_f32 v[222:223], v[222:223], 1.0 op_sel_hi:[1,0]
	v_pk_add_f32 v[224:225], v[224:225], 1.0 op_sel_hi:[1,0]
	v_pk_add_f32 v[226:227], v[226:227], 1.0 op_sel_hi:[1,0]
	v_rcp_f32_e32 v220, v220
	v_rcp_f32_e32 v221, v221
	v_rcp_f32_e32 v222, v222
	v_rcp_f32_e32 v223, v223
	v_rcp_f32_e32 v224, v224
	v_rcp_f32_e32 v225, v225
	v_rcp_f32_e32 v226, v226
	v_rcp_f32_e32 v227, v227
	v_pk_mul_f32 v[114:115], v[122:123], v[114:115]
	v_pk_mul_f32 v[116:117], v[124:125], v[116:117]
	v_pk_mul_f32 v[118:119], v[126:127], v[118:119]
	v_pk_mul_f32 v[120:121], v[128:129], v[120:121]
	v_pk_mul_f32 v[114:115], v[220:221], v[114:115]
	v_pk_mul_f32 v[116:117], v[222:223], v[116:117]
	v_pk_mul_f32 v[118:119], v[224:225], v[118:119]
	v_pk_mul_f32 v[120:121], v[226:227], v[120:121]
	v_cvt_pk_bf16_f32 v228, v118, v119
	v_cvt_pk_bf16_f32 v229, v120, v121
	v_cvt_pk_bf16_f32 v230, v114, v115
	v_cvt_pk_bf16_f32 v231, v116, v117
	v_lshl_or_b32 v146, s50, 7, v144
	v_lshl_add_u32 v150, s22, 8, v142
	v_ashrrev_i32_e32 v147, 31, v146
	v_mov_b64_e32 v[140:141], s[82:83]
	v_mad_i64_i32 v[148:149], s[24:25], v150, s54, v[140:141]
	v_lshlrev_b64 v[114:115], 1, v[146:147]
	v_lshl_add_u64 v[120:121], v[148:149], 0, v[114:115]
	global_store_dwordx4 v[120:121], v[228:231], off
	v_pk_mul_f32 v[220:221], v[106:107], s[100:101] op_sel_hi:[1,0]
	v_pk_mul_f32 v[222:223], v[108:109], s[100:101] op_sel_hi:[1,0]
	v_pk_mul_f32 v[224:225], v[110:111], s[100:101] op_sel_hi:[1,0]
	v_pk_mul_f32 v[226:227], v[112:113], s[100:101] op_sel_hi:[1,0]
	v_exp_f32_e32 v220, v220
	v_exp_f32_e32 v221, v221
	v_exp_f32_e32 v222, v222
	v_exp_f32_e32 v223, v223
	v_exp_f32_e32 v224, v224
	v_exp_f32_e32 v225, v225
	v_exp_f32_e32 v226, v226
	v_exp_f32_e32 v227, v227
	v_pk_add_f32 v[220:221], v[220:221], 1.0 op_sel_hi:[1,0]
	v_pk_add_f32 v[222:223], v[222:223], 1.0 op_sel_hi:[1,0]
	v_pk_add_f32 v[224:225], v[224:225], 1.0 op_sel_hi:[1,0]
	v_pk_add_f32 v[226:227], v[226:227], 1.0 op_sel_hi:[1,0]
	v_rcp_f32_e32 v220, v220
	v_rcp_f32_e32 v221, v221
	v_rcp_f32_e32 v222, v222
	v_rcp_f32_e32 v223, v223
	v_rcp_f32_e32 v224, v224
	v_rcp_f32_e32 v225, v225
	v_rcp_f32_e32 v226, v226
	v_rcp_f32_e32 v227, v227
	v_pk_mul_f32 v[98:99], v[106:107], v[98:99]
	v_pk_mul_f32 v[100:101], v[108:109], v[100:101]
	v_pk_mul_f32 v[102:103], v[110:111], v[102:103]
	v_pk_mul_f32 v[104:105], v[112:113], v[104:105]
	v_pk_mul_f32 v[98:99], v[220:221], v[98:99]
	v_pk_mul_f32 v[100:101], v[222:223], v[100:101]
	v_pk_mul_f32 v[102:103], v[224:225], v[102:103]
	v_pk_mul_f32 v[104:105], v[226:227], v[104:105]
	v_cvt_pk_bf16_f32 v232, v102, v103
	v_cvt_pk_bf16_f32 v233, v104, v105
	v_cvt_pk_bf16_f32 v234, v98, v99
	v_cvt_pk_bf16_f32 v235, v100, v101
	v_or_b32_e32 v116, 16, v150
	v_mad_i64_i32 v[116:117], s[24:25], v116, s54, v[140:141]
	v_lshl_add_u64 v[102:103], v[116:117], 0, v[114:115]
	global_store_dwordx4 v[102:103], v[232:235], off
	v_pk_mul_f32 v[220:221], v[90:91], s[100:101] op_sel_hi:[1,0]
	v_pk_mul_f32 v[222:223], v[92:93], s[100:101] op_sel_hi:[1,0]
	v_pk_mul_f32 v[224:225], v[94:95], s[100:101] op_sel_hi:[1,0]
	v_pk_mul_f32 v[226:227], v[96:97], s[100:101] op_sel_hi:[1,0]
	v_exp_f32_e32 v220, v220
	v_exp_f32_e32 v221, v221
	v_exp_f32_e32 v222, v222
	v_exp_f32_e32 v223, v223
	v_exp_f32_e32 v224, v224
	v_exp_f32_e32 v225, v225
	v_exp_f32_e32 v226, v226
	v_exp_f32_e32 v227, v227
	v_pk_add_f32 v[220:221], v[220:221], 1.0 op_sel_hi:[1,0]
	v_pk_add_f32 v[222:223], v[222:223], 1.0 op_sel_hi:[1,0]
	v_pk_add_f32 v[224:225], v[224:225], 1.0 op_sel_hi:[1,0]
	v_pk_add_f32 v[226:227], v[226:227], 1.0 op_sel_hi:[1,0]
	v_rcp_f32_e32 v220, v220
	v_rcp_f32_e32 v221, v221
	v_rcp_f32_e32 v222, v222
	v_rcp_f32_e32 v223, v223
	v_rcp_f32_e32 v224, v224
	v_rcp_f32_e32 v225, v225
	v_rcp_f32_e32 v226, v226
	v_rcp_f32_e32 v227, v227
	v_pk_mul_f32 v[82:83], v[90:91], v[82:83]
	v_pk_mul_f32 v[84:85], v[92:93], v[84:85]
	v_pk_mul_f32 v[86:87], v[94:95], v[86:87]
	v_pk_mul_f32 v[88:89], v[96:97], v[88:89]
	v_pk_mul_f32 v[82:83], v[220:221], v[82:83]
	v_pk_mul_f32 v[84:85], v[222:223], v[84:85]
	v_pk_mul_f32 v[86:87], v[224:225], v[86:87]
	v_pk_mul_f32 v[88:89], v[226:227], v[88:89]
	v_cvt_pk_bf16_f32 v228, v86, v87
	v_cvt_pk_bf16_f32 v229, v88, v89
	v_cvt_pk_bf16_f32 v230, v82, v83
	v_cvt_pk_bf16_f32 v231, v84, v85
	v_or_b32_e32 v98, 32, v150
	v_mad_i64_i32 v[98:99], s[24:25], v98, s54, v[140:141]
	v_lshl_add_u64 v[86:87], v[98:99], 0, v[114:115]
	global_store_dwordx4 v[86:87], v[228:231], off
	v_pk_mul_f32 v[220:221], v[74:75], s[100:101] op_sel_hi:[1,0]
	v_pk_mul_f32 v[222:223], v[76:77], s[100:101] op_sel_hi:[1,0]
	v_pk_mul_f32 v[224:225], v[78:79], s[100:101] op_sel_hi:[1,0]
	v_pk_mul_f32 v[226:227], v[80:81], s[100:101] op_sel_hi:[1,0]
	v_exp_f32_e32 v220, v220
	v_exp_f32_e32 v221, v221
	v_exp_f32_e32 v222, v222
	v_exp_f32_e32 v223, v223
	v_exp_f32_e32 v224, v224
	v_exp_f32_e32 v225, v225
	v_exp_f32_e32 v226, v226
	v_exp_f32_e32 v227, v227
	v_pk_add_f32 v[220:221], v[220:221], 1.0 op_sel_hi:[1,0]
	v_pk_add_f32 v[222:223], v[222:223], 1.0 op_sel_hi:[1,0]
	v_pk_add_f32 v[224:225], v[224:225], 1.0 op_sel_hi:[1,0]
	v_pk_add_f32 v[226:227], v[226:227], 1.0 op_sel_hi:[1,0]
	v_rcp_f32_e32 v220, v220
	v_rcp_f32_e32 v221, v221
	v_rcp_f32_e32 v222, v222
	v_rcp_f32_e32 v223, v223
	v_rcp_f32_e32 v224, v224
	v_rcp_f32_e32 v225, v225
	v_rcp_f32_e32 v226, v226
	v_rcp_f32_e32 v227, v227
	v_pk_mul_f32 v[66:67], v[74:75], v[66:67]
	v_pk_mul_f32 v[68:69], v[76:77], v[68:69]
	v_pk_mul_f32 v[70:71], v[78:79], v[70:71]
	v_pk_mul_f32 v[72:73], v[80:81], v[72:73]
	v_pk_mul_f32 v[66:67], v[220:221], v[66:67]
	v_pk_mul_f32 v[68:69], v[222:223], v[68:69]
	v_pk_mul_f32 v[70:71], v[224:225], v[70:71]
	v_pk_mul_f32 v[72:73], v[226:227], v[72:73]
	v_cvt_pk_bf16_f32 v232, v70, v71
	v_cvt_pk_bf16_f32 v233, v72, v73
	v_cvt_pk_bf16_f32 v234, v66, v67
	v_cvt_pk_bf16_f32 v235, v68, v69
	v_or_b32_e32 v82, 48, v150
	v_mad_i64_i32 v[82:83], s[24:25], v82, s54, v[140:141]
	v_lshl_add_u64 v[70:71], v[82:83], 0, v[114:115]
	global_store_dwordx4 v[70:71], v[232:235], off
	v_pk_mul_f32 v[220:221], v[58:59], s[100:101] op_sel_hi:[1,0]
	v_pk_mul_f32 v[222:223], v[60:61], s[100:101] op_sel_hi:[1,0]
	v_pk_mul_f32 v[224:225], v[62:63], s[100:101] op_sel_hi:[1,0]
	v_pk_mul_f32 v[226:227], v[64:65], s[100:101] op_sel_hi:[1,0]
	v_exp_f32_e32 v220, v220
	v_exp_f32_e32 v221, v221
	v_exp_f32_e32 v222, v222
	v_exp_f32_e32 v223, v223
	v_exp_f32_e32 v224, v224
	v_exp_f32_e32 v225, v225
	v_exp_f32_e32 v226, v226
	v_exp_f32_e32 v227, v227
	v_pk_add_f32 v[220:221], v[220:221], 1.0 op_sel_hi:[1,0]
	v_pk_add_f32 v[222:223], v[222:223], 1.0 op_sel_hi:[1,0]
	v_pk_add_f32 v[224:225], v[224:225], 1.0 op_sel_hi:[1,0]
	v_pk_add_f32 v[226:227], v[226:227], 1.0 op_sel_hi:[1,0]
	v_rcp_f32_e32 v220, v220
	v_rcp_f32_e32 v221, v221
	v_rcp_f32_e32 v222, v222
	v_rcp_f32_e32 v223, v223
	v_rcp_f32_e32 v224, v224
	v_rcp_f32_e32 v225, v225
	v_rcp_f32_e32 v226, v226
	v_rcp_f32_e32 v227, v227
	v_pk_mul_f32 v[50:51], v[58:59], v[50:51]
	v_pk_mul_f32 v[52:53], v[60:61], v[52:53]
	v_pk_mul_f32 v[54:55], v[62:63], v[54:55]
	v_pk_mul_f32 v[56:57], v[64:65], v[56:57]
	v_pk_mul_f32 v[50:51], v[220:221], v[50:51]
	v_pk_mul_f32 v[52:53], v[222:223], v[52:53]
	v_pk_mul_f32 v[54:55], v[224:225], v[54:55]
	v_pk_mul_f32 v[56:57], v[226:227], v[56:57]
	v_cvt_pk_bf16_f32 v228, v54, v55
	v_cvt_pk_bf16_f32 v229, v56, v57
	v_cvt_pk_bf16_f32 v230, v50, v51
	v_cvt_pk_bf16_f32 v231, v52, v53
	v_add_u32_e32 v66, 0x80, v150
	v_mad_i64_i32 v[66:67], s[24:25], v66, s54, v[140:141]
	v_lshl_add_u64 v[54:55], v[66:67], 0, v[114:115]
	global_store_dwordx4 v[54:55], v[228:231], off
	v_pk_mul_f32 v[220:221], v[42:43], s[100:101] op_sel_hi:[1,0]
	v_pk_mul_f32 v[222:223], v[44:45], s[100:101] op_sel_hi:[1,0]
	v_pk_mul_f32 v[224:225], v[46:47], s[100:101] op_sel_hi:[1,0]
	v_pk_mul_f32 v[226:227], v[48:49], s[100:101] op_sel_hi:[1,0]
	v_exp_f32_e32 v220, v220
	v_exp_f32_e32 v221, v221
	v_exp_f32_e32 v222, v222
	v_exp_f32_e32 v223, v223
	v_exp_f32_e32 v224, v224
	v_exp_f32_e32 v225, v225
	v_exp_f32_e32 v226, v226
	v_exp_f32_e32 v227, v227
	v_pk_add_f32 v[220:221], v[220:221], 1.0 op_sel_hi:[1,0]
	v_pk_add_f32 v[222:223], v[222:223], 1.0 op_sel_hi:[1,0]
	v_pk_add_f32 v[224:225], v[224:225], 1.0 op_sel_hi:[1,0]
	v_pk_add_f32 v[226:227], v[226:227], 1.0 op_sel_hi:[1,0]
	v_rcp_f32_e32 v220, v220
	v_rcp_f32_e32 v221, v221
	v_rcp_f32_e32 v222, v222
	v_rcp_f32_e32 v223, v223
	v_rcp_f32_e32 v224, v224
	v_rcp_f32_e32 v225, v225
	v_rcp_f32_e32 v226, v226
	v_rcp_f32_e32 v227, v227
	v_pk_mul_f32 v[34:35], v[42:43], v[34:35]
	v_pk_mul_f32 v[36:37], v[44:45], v[36:37]
	v_pk_mul_f32 v[38:39], v[46:47], v[38:39]
	v_pk_mul_f32 v[40:41], v[48:49], v[40:41]
	v_pk_mul_f32 v[34:35], v[220:221], v[34:35]
	v_pk_mul_f32 v[36:37], v[222:223], v[36:37]
	v_pk_mul_f32 v[38:39], v[224:225], v[38:39]
	v_pk_mul_f32 v[40:41], v[226:227], v[40:41]
	v_cvt_pk_bf16_f32 v232, v38, v39
	v_cvt_pk_bf16_f32 v233, v40, v41
	v_cvt_pk_bf16_f32 v234, v34, v35
	v_cvt_pk_bf16_f32 v235, v36, v37
	v_add_u32_e32 v50, 0x90, v150
	v_mad_i64_i32 v[50:51], s[24:25], v50, s54, v[140:141]
	v_lshl_add_u64 v[38:39], v[50:51], 0, v[114:115]
	global_store_dwordx4 v[38:39], v[232:235], off
	v_pk_mul_f32 v[220:221], v[26:27], s[100:101] op_sel_hi:[1,0]
	v_pk_mul_f32 v[222:223], v[28:29], s[100:101] op_sel_hi:[1,0]
	v_pk_mul_f32 v[224:225], v[30:31], s[100:101] op_sel_hi:[1,0]
	v_pk_mul_f32 v[226:227], v[32:33], s[100:101] op_sel_hi:[1,0]
	v_exp_f32_e32 v220, v220
	v_exp_f32_e32 v221, v221
	v_exp_f32_e32 v222, v222
	v_exp_f32_e32 v223, v223
	v_exp_f32_e32 v224, v224
	v_exp_f32_e32 v225, v225
	v_exp_f32_e32 v226, v226
	v_exp_f32_e32 v227, v227
	v_pk_add_f32 v[220:221], v[220:221], 1.0 op_sel_hi:[1,0]
	v_pk_add_f32 v[222:223], v[222:223], 1.0 op_sel_hi:[1,0]
	v_pk_add_f32 v[224:225], v[224:225], 1.0 op_sel_hi:[1,0]
	v_pk_add_f32 v[226:227], v[226:227], 1.0 op_sel_hi:[1,0]
	v_rcp_f32_e32 v220, v220
	v_rcp_f32_e32 v221, v221
	v_rcp_f32_e32 v222, v222
	v_rcp_f32_e32 v223, v223
	v_rcp_f32_e32 v224, v224
	v_rcp_f32_e32 v225, v225
	v_rcp_f32_e32 v226, v226
	v_rcp_f32_e32 v227, v227
	v_pk_mul_f32 v[18:19], v[26:27], v[18:19]
	v_pk_mul_f32 v[20:21], v[28:29], v[20:21]
	v_pk_mul_f32 v[22:23], v[30:31], v[22:23]
	v_pk_mul_f32 v[24:25], v[32:33], v[24:25]
	v_pk_mul_f32 v[18:19], v[220:221], v[18:19]
	v_pk_mul_f32 v[20:21], v[222:223], v[20:21]
	v_pk_mul_f32 v[22:23], v[224:225], v[22:23]
	v_pk_mul_f32 v[24:25], v[226:227], v[24:25]
	v_cvt_pk_bf16_f32 v228, v22, v23
	v_cvt_pk_bf16_f32 v229, v24, v25
	v_cvt_pk_bf16_f32 v230, v18, v19
	v_cvt_pk_bf16_f32 v231, v20, v21
	v_add_u32_e32 v34, 0xa0, v150
	v_mad_i64_i32 v[34:35], s[24:25], v34, s54, v[140:141]
	v_lshl_add_u64 v[22:23], v[34:35], 0, v[114:115]
	global_store_dwordx4 v[22:23], v[228:231], off
	v_pk_mul_f32 v[220:221], v[10:11], s[100:101] op_sel_hi:[1,0]
	v_pk_mul_f32 v[222:223], v[12:13], s[100:101] op_sel_hi:[1,0]
	v_pk_mul_f32 v[224:225], v[14:15], s[100:101] op_sel_hi:[1,0]
	v_pk_mul_f32 v[226:227], v[16:17], s[100:101] op_sel_hi:[1,0]
	v_exp_f32_e32 v220, v220
	v_exp_f32_e32 v221, v221
	v_exp_f32_e32 v222, v222
	v_exp_f32_e32 v223, v223
	v_exp_f32_e32 v224, v224
	v_exp_f32_e32 v225, v225
	v_exp_f32_e32 v226, v226
	v_exp_f32_e32 v227, v227
	v_pk_add_f32 v[220:221], v[220:221], 1.0 op_sel_hi:[1,0]
	v_pk_add_f32 v[222:223], v[222:223], 1.0 op_sel_hi:[1,0]
	v_pk_add_f32 v[224:225], v[224:225], 1.0 op_sel_hi:[1,0]
	v_pk_add_f32 v[226:227], v[226:227], 1.0 op_sel_hi:[1,0]
	v_rcp_f32_e32 v220, v220
	v_rcp_f32_e32 v221, v221
	v_rcp_f32_e32 v222, v222
	v_rcp_f32_e32 v223, v223
	v_rcp_f32_e32 v224, v224
	v_rcp_f32_e32 v225, v225
	v_rcp_f32_e32 v226, v226
	v_rcp_f32_e32 v227, v227
	v_pk_mul_f32 v[2:3], v[10:11], v[2:3]
	v_pk_mul_f32 v[4:5], v[12:13], v[4:5]
	v_pk_mul_f32 v[6:7], v[14:15], v[6:7]
	v_pk_mul_f32 v[8:9], v[16:17], v[8:9]
	v_pk_mul_f32 v[2:3], v[220:221], v[2:3]
	v_pk_mul_f32 v[4:5], v[222:223], v[4:5]
	v_pk_mul_f32 v[6:7], v[224:225], v[6:7]
	v_pk_mul_f32 v[8:9], v[226:227], v[8:9]
	v_cvt_pk_bf16_f32 v232, v6, v7
	v_cvt_pk_bf16_f32 v233, v8, v9
	v_cvt_pk_bf16_f32 v234, v2, v3
	v_cvt_pk_bf16_f32 v235, v4, v5
	v_add_u32_e32 v18, 0xb0, v150
	v_mad_i64_i32 v[18:19], s[24:25], v18, s54, v[140:141]
	v_lshl_add_u64 v[6:7], v[18:19], 0, v[114:115]
	s_andn2_b64 vcc, exec, s[6:7]
	s_mov_b64 s[6:7], -1
	s_mov_b32 s72, 0x24000
	s_movk_i32 s63, 0x9ff
	s_mov_b64 s[70:71], 0x800
	global_store_dwordx4 v[6:7], v[232:235], off
	s_cbranch_vccnz .LBB0_994
	s_andn2_b64 vcc, exec, s[8:9]
	s_cbranch_vccnz .LBB0_993
	s_barrier
	s_branch .LBB0_993
